# k28: k23 + FFN-up epilogue VALU peepholes (mov+pk_mul+add+add -> 2 fma, broadcast movs -> op_sel_hi, redundant s_nop removal)
# speedup vs baseline: 1.0265x; 1.0018x over previous
; __device__ __forceinline__ float dpp_row_shr1(float x) { return __builtin_bit_cast(float, __builtin_amdgcn_update_dpp(__builtin_bit_cast(int, x), __builtin_bit_cast(int, x), 0x111, 0xf, 0xf, false)); }
;     __device__ __forceinline__ void operator()(f32x4 (&acc)[2][2][4][2], const pg8::Unit& u, int wr, int wc, int fr, int fq) const {
;     ...
;         for (int k = 0; k < 8; ++k) { const float rs = __builtin_amdgcn_rsqf(__hip_atomic_load(ssq + tok0 + k, __ATOMIC_RELAXED, __HIP_MEMORY_SCOPE_AGENT) * (1.0f / 1024.0f) + 1e-6f);
; #pragma unroll
;             for (int bj = 0; bj < 2; ++bj) { acc[k >> 2][bj][k & 3][0] = acc[k >> 2][bj][k & 3][0] * rs; acc[k >> 2][bj][k & 3][1] = acc[k >> 2][bj][k & 3][1] * rs; } }
;         const int grp = 2 * u.pm + wr;
;         const bool samp = (u.pm >= 64 && u.pm < PM_META), meta = (u.pm == PM_META);
;         const int sb = 32 * (u.pm - 64) + 16 * wr + fr;
;         const bool defer = (!samp && !meta && fr == 0);
;         const bool lastlane = meta ? (wr == 0 && fr == 1) : (!samp && fr == 15);
;         f32x4 w0[2], w1[2], w2[2], bb[2], p6[2], p7[2];
; #pragma unroll
;         for (int n = 0; n < 2; ++n) {
;             const int c4 = ch0 + 4 * n;
;             w0[n] = *(const f32x4*)(cw + c4); w1[n] = *(const f32x4*)(cw + DFF + c4); w2[n] = *(const f32x4*)(cw + 2 * DFF + c4); bb[n] = *(const f32x4*)(cb + c4);
; #pragma unroll
;             for (int e = 0; e < 4; ++e) { p6[n][e] = dpp_row_shr1(acc[1][0][2][n][e]); p7[n][e] = dpp_row_shr1(acc[1][0][3][n][e]); }
.LBB0_479:
	v_mov_b32_e32 v16, v240
	v_mov_b32_e32 v17, v241
	v_mov_b32_e32 v18, v242
	v_mov_b32_e32 v19, v243
	v_mov_b32_e32 v20, v244
	v_mov_b32_e32 v21, v245
	v_mov_b32_e32 v22, v246
	v_mov_b32_e32 v23, v247
	v_mov_b32_e32 v140, v168
	v_mov_b32_e32 v141, v169
	v_mov_b32_e32 v142, v170
	v_mov_b32_e32 v143, v171
	v_mov_b32_e32 v24, v164
	v_mov_b32_e32 v25, v165
	v_mov_b32_e32 v26, v166
	v_mov_b32_e32 v27, v167
	v_mov_b32_e32 v193, v192
	v_mov_b32_e32 v191, v190
	v_pk_mul_f32 v[34:35], v[34:35], v[192:193] op_sel_hi:[1,0]
	v_pk_mul_f32 v[32:33], v[32:33], v[192:193]
	v_pk_mul_f32 v[42:43], v[42:43], v[190:191] op_sel_hi:[1,0]
	v_pk_mul_f32 v[40:41], v[40:41], v[190:191]
	v_mov_b32_e32 v168, v32
	v_mov_b32_e32 v164, v40
	v_mov_b32_e32 v169, v33
	v_mov_b32_e32 v165, v41
	v_mov_b32_e32 v170, v34
	v_mov_b32_e32 v166, v42
	v_mov_b32_e32 v171, v35
	v_mov_b32_e32 v167, v43
	v_mov_b32_dpp v168, v168 row_shr:1 row_mask:0xf bank_mask:0xf
	v_mov_b32_dpp v164, v164 row_shr:1 row_mask:0xf bank_mask:0xf
	v_mov_b32_dpp v169, v169 row_shr:1 row_mask:0xf bank_mask:0xf
	v_mov_b32_dpp v165, v165 row_shr:1 row_mask:0xf bank_mask:0xf
	v_mov_b32_dpp v170, v170 row_shr:1 row_mask:0xf bank_mask:0xf
	v_mov_b32_dpp v166, v166 row_shr:1 row_mask:0xf bank_mask:0xf
	v_mov_b32_dpp v171, v171 row_shr:1 row_mask:0xf bank_mask:0xf
	s_and_b64 vcc, exec, s[12:13]
	v_mov_b32_dpp v167, v167 row_shr:1 row_mask:0xf bank_mask:0xf
	s_cbranch_vccnz .LBB0_498
	global_load_dwordx4 v[168:171], v[198:199], off offset:16
	global_load_dwordx4 v[164:167], v[200:201], off offset:16
	s_and_saveexec_b64 s[46:47], s[0:1]
	s_cbranch_execnz .LBB0_499

; __device__ __forceinline__ unsigned cvt_pk_bf16(float lo, float hi) { unsigned r; asm volatile("v_cvt_pk_bf16_f32 %0, %1, %2" : "=v"(r) : "v"(lo), "v"(hi)); return r; }
; __device__ __forceinline__ float siluf_(float x) { return x * __builtin_amdgcn_rcpf(1.f + __expf(-x)); }
;     __device__ __forceinline__ void operator()(f32x4 (&acc)[2][2][4][2], const pg8::Unit& u, int wr, int wc, int fr, int fq) const {
;     ...
;         for (int k = 0; k < 8; ++k) {
;             unsigned hw[4];
; #pragma unroll
;             for (int n = 0; n < 2; ++n) {
;                 const f32x4 uk = acc[k >> 2][0][k & 3][n], gk = acc[k >> 2][1][k & 3][n];
;                 const f32x4 um1 = (k >= 1) ? acc[(k - 1 < 0 ? 0 : k - 1) >> 2][0][(k - 1 < 0 ? 0 : k - 1) & 3][n] : p7[n];
;                 const f32x4 um2 = (k >= 2) ? acc[(k - 2 < 0 ? 0 : k - 2) >> 2][0][(k - 2 < 0 ? 0 : k - 2) & 3][n] : (k == 1 ? p7[n] : p6[n]);
;                 const f32x4 cv = bb[n] + w0[n] * um2 + w1[n] * um1 + w2[n] * uk;
;                 f32x4 hv;
; #pragma unroll
;                 for (int e = 0; e < 4; ++e) hv[e] = siluf_(cv[e]) * gk[e];
;                 hw[2 * n] = pg8::cvt_pk_bf16(hv[0], hv[1]); hw[2 * n + 1] = pg8::cvt_pk_bf16(hv[2], hv[3]);
;                 if (defer && k < 2) {
;                     *(f32x4*)(sbf + (size_t)((grp * 2 + k) * 2 + 0) * DFF + ch0 + 4 * n) = uk;
;                     *(f32x4*)(sbf + (size_t)((grp * 2 + k) * 2 + 1) * DFF + ch0 + 4 * n) = gk;
;                 }
;             }
;             if (!(defer && k < 2)) *(u32x4*)(H + (size_t)(tok0 + k) * DFF + ch0) = (u32x4){hw[0], hw[1], hw[2], hw[3]};
.LBB0_483:
	s_and_b64 s[12:13], s[6:7], s[10:11]
	s_waitcnt vmcnt(4)
	v_cndmask_b32_e64 v201, v172, 0, s[12:13]
	v_fmamk_f32 v172, v239, 0x3a800000, v211
	v_rsq_f32_e32 v202, v172
	v_cndmask_b32_e64 v203, v179, 0, s[12:13]
	v_cndmask_b32_e64 v176, v176, 0, s[12:13]
	v_cndmask_b32_e64 v199, v173, 0, s[12:13]
	v_pk_mul_f32 v[152:153], v[152:153], v[202:203] op_sel_hi:[1,0]
	v_pk_mul_f32 v[172:173], v[156:157], v[202:203] op_sel_hi:[1,0]
	v_cndmask_b32_e64 v198, v177, 0, s[12:13]
	v_cndmask_b32_e64 v177, v175, 0, s[12:13]
	v_cndmask_b32_e64 v179, v174, 0, s[12:13]
	v_pk_mul_f32 v[174:175], v[158:159], v[202:203] op_sel_hi:[1,0]
	v_fma_f32 v158, v12, v176, v8
	v_fma_f32 v159, v13, v198, v9
	v_fma_f32 v157, v4, v201, v158
	v_fma_f32 v156, v152, v160, v157
	v_mul_f32_e32 v157, 0xbfb8aa3b, v156
	v_exp_f32_e32 v157, v157
	v_mov_b32_e32 v198, v161
	v_cndmask_b32_e64 v178, v178, 0, s[12:13]
	v_pk_mul_f32 v[154:155], v[154:155], v[202:203] op_sel_hi:[1,0]
	v_add_f32_e32 v157, 1.0, v157
	v_rcp_f32_e32 v157, v157
	v_fma_f32 v176, v14, v178, v10
	v_mov_b32_e32 v178, v162
	s_add_i32 s0, s96, 0xffffffbb
	v_mul_f32_e32 v156, v156, v157
	v_mul_f32_e32 v158, v172, v156
	v_mov_b32_e32 v156, v153
	v_mov_b32_e32 v157, v5
	v_pk_mul_f32 v[156:157], v[156:157], v[198:199]
	v_fma_f32 v198, v15, v203, v11
	v_add_f32_e32 v157, v157, v159
	v_add_f32_e32 v156, v156, v157
	v_mul_f32_e32 v157, 0xbfb8aa3b, v156
	v_exp_f32_e32 v157, v157
	s_cmp_lt_u32 s0, -5
	s_cselect_b64 s[0:1], -1, 0
	s_lshl_b32 s21, s45, 2
	v_add_f32_e32 v157, 1.0, v157
	v_rcp_f32_e32 v157, v157
	s_or_b32 s46, s21, 1
	s_and_b64 s[0:1], s[4:5], s[0:1]
	s_mul_i32 s47, s45, 0xb000
	v_mul_f32_e32 v156, v156, v157
	v_mul_f32_e32 v159, v173, v156
	s_mul_hi_i32 s67, s21, 0x2c00
	v_fma_f32 v157, v6, v179, v176
	v_fma_f32 v156, v154, v178, v157
	v_mul_f32_e32 v157, 0xbfb8aa3b, v156
	v_exp_f32_e32 v157, v157
	s_mul_hi_i32 s45, s46, 0x2c00
	s_mulk_i32 s46, 0x2c00
	v_add_f32_e32 v157, 1.0, v157
	v_rcp_f32_e32 v157, v157
	s_nop 0
	v_mul_f32_e32 v156, v156, v157
	v_mul_f32_e32 v178, v174, v156
	v_fma_f32 v157, v7, v177, v198
	v_fma_f32 v156, v155, v163, v157
	v_mul_f32_e32 v157, 0xbfb8aa3b, v156
	v_exp_f32_e32 v157, v157
	s_nop 0
	v_add_f32_e32 v157, 1.0, v157
	v_rcp_f32_e32 v157, v157
	s_nop 0
	v_mul_f32_e32 v156, v156, v157
	v_mul_f32_e32 v157, v175, v156
	v_cvt_pk_bf16_f32 v156, v158, v159
	v_cvt_pk_bf16_f32 v157, v178, v157
	s_and_saveexec_b64 s[10:11], s[0:1]
	s_cbranch_execz .LBB0_485
	s_add_u32 s68, s30, s46
	s_addc_u32 s69, s31, s45
	v_lshl_add_u64 v[158:159], s[68:69], 0, v[194:195]
	s_add_u32 s68, s30, s47
	s_addc_u32 s69, s31, s67
	v_lshl_add_u64 v[204:205], s[68:69], 0, v[194:195]
	global_store_dwordx4 v[204:205], v[152:155], off
	global_store_dwordx4 v[158:159], v[172:175], off
.LBB0_485:
	s_or_b64 exec, exec, s[10:11]
	s_waitcnt vmcnt(1)
	v_cndmask_b32_e64 v175, v168, 0, s[12:13]
	v_mov_b32_e32 v203, v202
	v_cndmask_b32_e64 v174, v169, 0, s[12:13]
	s_waitcnt vmcnt(0)
	v_cndmask_b32_e64 v169, v164, 0, s[12:13]
	v_pk_mul_f32 v[150:151], v[150:151], v[202:203] op_sel_hi:[1,0]
	v_pk_mul_f32 v[146:147], v[146:147], v[202:203] op_sel_hi:[1,0]
	v_fma_f32 v158, v16, v175, v24
	v_pk_mul_f32 v[148:149], v[148:149], v[202:203]
	v_fmac_f32_e32 v158, v20, v169
	v_fmac_f32_e32 v158, v148, v140
	v_mul_f32_e32 v159, 0xbfb8aa3b, v158
	v_exp_f32_e32 v159, v159
	v_cndmask_b32_e64 v168, v165, 0, s[12:13]
	v_cndmask_b32_e64 v170, v170, 0, s[12:13]
	v_cndmask_b32_e64 v166, v166, 0, s[12:13]
	v_add_f32_e32 v159, 1.0, v159
	v_rcp_f32_e32 v159, v159
	v_cndmask_b32_e64 v171, v171, 0, s[12:13]
	v_cndmask_b32_e64 v167, v167, 0, s[12:13]
	s_xor_b64 s[10:11], s[0:1], -1
	v_mul_f32_e32 v158, v158, v159
	v_fma_f32 v159, v17, v174, v25
	v_fmac_f32_e32 v159, v21, v168
	v_fmac_f32_e32 v159, v149, v141
	v_mul_f32_e32 v164, 0xbfb8aa3b, v159
	v_exp_f32_e32 v164, v164
	s_cmp_lt_i32 s96, 64
	s_mov_b32 s68, 0x5900000
	s_cselect_b32 s68, s68, 0xd500000
	v_add_f32_e32 v164, 1.0, v164
	v_rcp_f32_e32 v164, v164
	s_add_u32 s68, s94, s68
	s_addc_u32 s69, s95, 0
	v_pk_mul_f32 v[144:145], v[144:145], v[202:203]
	v_mul_f32_e32 v159, v159, v164
	v_fma_f32 v164, v18, v170, v26
	v_fmac_f32_e32 v164, v22, v166
	v_fmac_f32_e32 v164, v150, v142
	v_mul_f32_e32 v165, 0xbfb8aa3b, v164
	v_exp_f32_e32 v165, v165
	v_lshl_add_u64 v[172:173], v[196:197], 1, s[68:69]
	v_mul_f32_e32 v158, v144, v158
	v_mul_f32_e32 v159, v145, v159
	v_add_f32_e32 v165, 1.0, v165
	v_rcp_f32_e32 v165, v165
	v_cvt_pk_bf16_f32 v158, v158, v159
	s_nop 0
	v_mul_f32_e32 v164, v164, v165
	v_fma_f32 v165, v19, v171, v27
	v_fmac_f32_e32 v165, v23, v167
	v_fmac_f32_e32 v165, v151, v143
	v_mul_f32_e32 v170, 0xbfb8aa3b, v165
	v_exp_f32_e32 v170, v170
	v_mul_f32_e32 v164, v146, v164
	v_add_f32_e32 v170, 1.0, v170
	v_rcp_f32_e32 v170, v170
	s_nop 0
	v_mul_f32_e32 v165, v165, v170
	v_mul_f32_e32 v165, v147, v165
	v_cvt_pk_bf16_f32 v159, v164, v165
	s_and_saveexec_b64 s[12:13], s[10:11]
	s_xor_b64 s[12:13], exec, s[12:13]
	s_cbranch_execz .LBB0_487
	s_movk_i32 s42, 0x1600
	v_mad_i64_i32 v[144:145], s[68:69], v188, s42, v[172:173]
	global_store_dwordx4 v[144:145], v[156:159], off

; __device__ __forceinline__ unsigned cvt_pk_bf16(float lo, float hi) { unsigned r; asm volatile("v_cvt_pk_bf16_f32 %0, %1, %2" : "=v"(r) : "v"(lo), "v"(hi)); return r; }
; __device__ __forceinline__ float siluf_(float x) { return x * __builtin_amdgcn_rcpf(1.f + __expf(-x)); }
;     __device__ __forceinline__ void operator()(f32x4 (&acc)[2][2][4][2], const pg8::Unit& u, int wr, int wc, int fr, int fq) const {
;     ...
;         for (int k = 0; k < 8; ++k) {
;             unsigned hw[4];
; #pragma unroll
;             for (int n = 0; n < 2; ++n) {
;                 const f32x4 uk = acc[k >> 2][0][k & 3][n], gk = acc[k >> 2][1][k & 3][n];
;                 const f32x4 um1 = (k >= 1) ? acc[(k - 1 < 0 ? 0 : k - 1) >> 2][0][(k - 1 < 0 ? 0 : k - 1) & 3][n] : p7[n];
;                 const f32x4 um2 = (k >= 2) ? acc[(k - 2 < 0 ? 0 : k - 2) >> 2][0][(k - 2 < 0 ? 0 : k - 2) & 3][n] : (k == 1 ? p7[n] : p6[n]);
;                 const f32x4 cv = bb[n] + w0[n] * um2 + w1[n] * um1 + w2[n] * uk;
;                 f32x4 hv;
; #pragma unroll
;                 for (int e = 0; e < 4; ++e) hv[e] = siluf_(cv[e]) * gk[e];
;                 hw[2 * n] = pg8::cvt_pk_bf16(hv[0], hv[1]); hw[2 * n + 1] = pg8::cvt_pk_bf16(hv[2], hv[3]);
;                 if (defer && k < 2) {
;                     *(f32x4*)(sbf + (size_t)((grp * 2 + k) * 2 + 0) * DFF + ch0 + 4 * n) = uk;
;                     *(f32x4*)(sbf + (size_t)((grp * 2 + k) * 2 + 1) * DFF + ch0 + 4 * n) = gk;
;                 }
;             }
;             if (!(defer && k < 2)) *(u32x4*)(H + (size_t)(tok0 + k) * DFF + ch0) = (u32x4){hw[0], hw[1], hw[2], hw[3]};
.LBB0_489:
	s_or_b64 exec, exec, s[12:13]
	s_nop 0
	v_fmamk_f32 v144, v238, 0x3a800000, v211
	v_rsq_f32_e32 v164, v144
	v_mov_b32_e32 v156, v160
	v_mov_b32_e32 v157, v4
	v_mov_b32_e32 v158, v162
	v_pk_mul_f32 v[136:137], v[136:137], v[164:165] op_sel_hi:[1,0]
	v_pk_mul_f32 v[144:145], v[132:133], v[164:165] op_sel_hi:[1,0]
	v_pk_mul_f32 v[146:147], v[134:135], v[164:165] op_sel_hi:[1,0]
	v_fma_f32 v134, v12, v201, v8
	v_fma_f32 v135, v13, v199, v9
	v_fma_f32 v4, v152, v157, v134
	v_fma_f32 v4, v136, v156, v4
	v_mul_f32_e32 v132, 0xbfb8aa3b, v4
	v_exp_f32_e32 v132, v132
	v_pk_mul_f32 v[138:139], v[138:139], v[164:165] op_sel_hi:[1,0]
	v_mov_b32_e32 v159, v6
	v_add_f32_e32 v132, 1.0, v132
	v_rcp_f32_e32 v132, v132
	v_fma_f32 v160, v14, v179, v10
	s_or_b32 s47, s21, 2
	s_or_b32 s45, s21, 3
	v_mul_f32_e32 v4, v4, v132
	v_mul_f32_e32 v134, v144, v4
	v_mov_b32_e32 v4, v161
	v_fma_f32 v161, v15, v177, v11
	v_fma_f32 v133, v153, v5, v135
	v_fma_f32 v132, v137, v4, v133
	v_mul_f32_e32 v133, 0xbfb8aa3b, v132
	v_exp_f32_e32 v133, v133
	s_mul_hi_i32 s46, s47, 0x2c00
	s_mulk_i32 s47, 0x2c00
	s_mul_hi_i32 s21, s45, 0x2c00
	v_add_f32_e32 v133, 1.0, v133
	v_rcp_f32_e32 v133, v133
	s_mulk_i32 s45, 0x2c00
	v_mul_f32_e32 v132, v132, v133
	v_mul_f32_e32 v135, v145, v132
	v_fma_f32 v6, v154, v159, v160
	v_fma_f32 v6, v138, v158, v6
	v_mul_f32_e32 v132, 0xbfb8aa3b, v6
	v_exp_f32_e32 v132, v132
	s_nop 0
	v_add_f32_e32 v132, 1.0, v132
	v_rcp_f32_e32 v132, v132
	s_nop 0
	v_mul_f32_e32 v6, v6, v132
	v_mul_f32_e32 v160, v146, v6
	v_mov_b32_e32 v6, v163
	v_fma_f32 v133, v155, v7, v161
	v_fma_f32 v132, v139, v6, v133
	v_mul_f32_e32 v133, 0xbfb8aa3b, v132
	v_exp_f32_e32 v133, v133
	s_nop 0
	v_add_f32_e32 v133, 1.0, v133
	v_rcp_f32_e32 v133, v133
	s_nop 0
	v_mul_f32_e32 v132, v132, v133
	v_mul_f32_e32 v133, v147, v132
	v_cvt_pk_bf16_f32 v132, v134, v135
	v_cvt_pk_bf16_f32 v133, v160, v133
	s_and_saveexec_b64 s[12:13], s[0:1]
	v_readlane_b32 s68, v253, 37
	v_readlane_b32 s71, v253, 40
	v_readlane_b32 s69, v253, 38
	v_readlane_b32 s70, v253, 39
	s_cbranch_execz .LBB0_491
	s_add_u32 s0, s30, s45
	s_addc_u32 s1, s31, s21
	v_lshl_add_u64 v[134:135], s[0:1], 0, v[194:195]
	s_add_u32 s0, s30, s47
	s_addc_u32 s1, s31, s46
	v_lshl_add_u64 v[160:161], s[0:1], 0, v[194:195]
	global_store_dwordx4 v[160:161], v[136:139], off
	global_store_dwordx4 v[134:135], v[144:147], off
.LBB0_491:
	s_or_b64 exec, exec, s[12:13]
	v_mov_b32_e32 v165, v164
	v_pk_mul_f32 v[130:131], v[130:131], v[164:165] op_sel_hi:[1,0]
	v_pk_mul_f32 v[126:127], v[126:127], v[164:165] op_sel_hi:[1,0]
	v_fma_f32 v134, v16, v169, v24
	v_pk_mul_f32 v[128:129], v[128:129], v[164:165]
	v_fmac_f32_e32 v134, v148, v20
	v_fmac_f32_e32 v134, v128, v140
	v_mul_f32_e32 v135, 0xbfb8aa3b, v134
	v_exp_f32_e32 v135, v135
	v_pk_mul_f32 v[124:125], v[124:125], v[164:165]
	v_add_f32_e32 v135, 1.0, v135
	v_rcp_f32_e32 v135, v135
	s_nop 0
	v_mul_f32_e32 v134, v134, v135
	v_fma_f32 v135, v17, v168, v25
	v_fmac_f32_e32 v135, v149, v21
	v_fmac_f32_e32 v135, v129, v141
	v_mul_f32_e32 v144, 0xbfb8aa3b, v135
	v_exp_f32_e32 v144, v144
	v_mul_f32_e32 v134, v124, v134
	v_add_f32_e32 v144, 1.0, v144
	v_rcp_f32_e32 v144, v144
	s_nop 0
	v_mul_f32_e32 v135, v135, v144
	v_fma_f32 v144, v18, v166, v26
	v_fmac_f32_e32 v144, v150, v22
	v_fmac_f32_e32 v144, v130, v142
	v_mul_f32_e32 v145, 0xbfb8aa3b, v144
	v_exp_f32_e32 v145, v145
	v_mul_f32_e32 v135, v125, v135
	v_cvt_pk_bf16_f32 v134, v134, v135
	v_add_f32_e32 v145, 1.0, v145
	v_rcp_f32_e32 v145, v145
	s_nop 0
	v_mul_f32_e32 v144, v144, v145
	v_fma_f32 v145, v19, v167, v27
	v_fmac_f32_e32 v145, v151, v23
	v_fmac_f32_e32 v145, v131, v143
	v_mul_f32_e32 v146, 0xbfb8aa3b, v145
	v_exp_f32_e32 v146, v146
	v_mul_f32_e32 v144, v126, v144
	v_add_f32_e32 v146, 1.0, v146
	v_rcp_f32_e32 v146, v146
	s_nop 0
	v_mul_f32_e32 v145, v145, v146
	v_mul_f32_e32 v145, v127, v145
	v_cvt_pk_bf16_f32 v135, v144, v145
	s_and_saveexec_b64 s[0:1], s[10:11]
	s_xor_b64 s[0:1], exec, s[0:1]
	s_cbranch_execz .LBB0_493
	v_or_b32_e32 v124, 1, v188
	s_movk_i32 s10, 0x1600
	v_mad_i64_i32 v[124:125], s[10:11], v124, s10, v[172:173]
	global_store_dwordx4 v[124:125], v[132:135], off

;     __device__ __forceinline__ void operator()(f32x4 (&acc)[2][2][4][2], const pg8::Unit& u, int wr, int wc, int fr, int fq) const {
;     ...
;         for (int k = 0; k < 8; ++k) { const float rs = __builtin_amdgcn_rsqf(__hip_atomic_load(ssq + tok0 + k, __ATOMIC_RELAXED, __HIP_MEMORY_SCOPE_AGENT) * (1.0f / 1024.0f) + 1e-6f);
; #pragma unroll
;             for (int bj = 0; bj < 2; ++bj) { acc[k >> 2][bj][k & 3][0] = acc[k >> 2][bj][k & 3][0] * rs; acc[k >> 2][bj][k & 3][1] = acc[k >> 2][bj][k & 3][1] * rs; } }
;         const int grp = 2 * u.pm + wr;
;         const bool samp = (u.pm >= 64 && u.pm < PM_META), meta = (u.pm == PM_META);
;         const int sb = 32 * (u.pm - 64) + 16 * wr + fr;
;         const bool defer = (!samp && !meta && fr == 0);
;         const bool lastlane = meta ? (wr == 0 && fr == 1) : (!samp && fr == 15);
;         f32x4 w0[2], w1[2], w2[2], bb[2], p6[2], p7[2];
; #pragma unroll
;         for (int n = 0; n < 2; ++n) {
;             const int c4 = ch0 + 4 * n;
;             w0[n] = *(const f32x4*)(cw + c4); w1[n] = *(const f32x4*)(cw + DFF + c4); w2[n] = *(const f32x4*)(cw + 2 * DFF + c4); bb[n] = *(const f32x4*)(cb + c4);
; #pragma unroll
;             for (int e = 0; e < 4; ++e) { p6[n][e] = dpp_row_shr1(acc[1][0][2][n][e]); p7[n][e] = dpp_row_shr1(acc[1][0][3][n][e]); }
;             if (samp) { p6[n] = *(const f32x4*)(cst + (size_t)(sb * 2 + 0) * DFF + c4); p7[n] = *(const f32x4*)(cst + (size_t)(sb * 2 + 1) * DFF + c4); }
;             if (meta && wr == 0 && fr == 0) { p6[n] = (f32x4){0.f, 0.f, 0.f, 0.f}; p7[n] = p6[n]; }
;             if (lastlane) { *(f32x4*)(sbl + (size_t)(grp * 2 + 0) * DFF + c4) = acc[1][0][2][n]; *(f32x4*)(sbl + (size_t)(grp * 2 + 1) * DFF + c4) = acc[1][0][3][n]; }
;             if (samp) { *(f32x4*)(cso + (size_t)(sb * 2 + 0) * DFF + c4) = acc[1][0][2][n]; *(f32x4*)(cso + (size_t)(sb * 2 + 1) * DFF + c4) = acc[1][0][3][n]; }
;         }
; #pragma unroll
;         for (int k = 0; k < 8; ++k) {
;             unsigned hw[4];
; #pragma unroll
;             for (int n = 0; n < 2; ++n) {
;                 const f32x4 uk = acc[k >> 2][0][k & 3][n], gk = acc[k >> 2][1][k & 3][n];
;                 const f32x4 um1 = (k >= 1) ? acc[(k - 1 < 0 ? 0 : k - 1) >> 2][0][(k - 1 < 0 ? 0 : k - 1) & 3][n] : p7[n];
.LBB0_495:
	s_or_b64 exec, exec, s[0:1]
	s_nop 0
	v_fmamk_f32 v124, v237, 0x3a800000, v211
	v_rsq_f32_e32 v126, v124
	s_movk_i32 s10, 0x1600
	v_pk_mul_f32 v[48:49], v[48:49], v[190:191]
	v_pk_mul_f32 v[44:45], v[44:45], v[190:191]
	v_pk_mul_f32 v[124:125], v[114:115], v[126:127] op_sel_hi:[1,0]
	v_pk_mul_f32 v[114:115], v[108:109], v[126:127] op_sel_hi:[1,0]
	v_fmamk_f32 v108, v236, 0x3a800000, v211
	v_pk_mul_f32 v[122:123], v[122:123], v[126:127] op_sel_hi:[1,0]
	v_pk_mul_f32 v[120:121], v[120:121], v[126:127] op_sel_hi:[1,0]
	v_pk_mul_f32 v[118:119], v[118:119], v[126:127] op_sel_hi:[1,0]
	v_pk_mul_f32 v[116:117], v[116:117], v[126:127] op_sel_hi:[1,0]
	v_pk_mul_f32 v[132:133], v[112:113], v[126:127] op_sel_hi:[1,0]
	v_pk_mul_f32 v[112:113], v[110:111], v[126:127] op_sel_hi:[1,0]
	v_rsq_f32_e32 v126, v108
	s_andn2_b64 vcc, exec, s[8:9]
	v_pk_mul_f32 v[108:109], v[98:99], v[126:127] op_sel_hi:[1,0]
	v_pk_mul_f32 v[98:99], v[92:93], v[126:127] op_sel_hi:[1,0]
	v_fmamk_f32 v92, v235, 0x3a800000, v211
	v_pk_mul_f32 v[106:107], v[106:107], v[126:127] op_sel_hi:[1,0]
	v_pk_mul_f32 v[104:105], v[104:105], v[126:127] op_sel_hi:[1,0]
	v_pk_mul_f32 v[102:103], v[102:103], v[126:127] op_sel_hi:[1,0]
	v_pk_mul_f32 v[100:101], v[100:101], v[126:127] op_sel_hi:[1,0]
	v_pk_mul_f32 v[110:111], v[96:97], v[126:127] op_sel_hi:[1,0]
	v_pk_mul_f32 v[96:97], v[94:95], v[126:127] op_sel_hi:[1,0]
	v_rsq_f32_e32 v126, v92
	s_nop 0
	v_pk_mul_f32 v[92:93], v[82:83], v[126:127] op_sel_hi:[1,0]
	v_pk_mul_f32 v[82:83], v[76:77], v[126:127] op_sel_hi:[1,0]
	v_fmamk_f32 v76, v189, 0x3a800000, v211
	v_pk_mul_f32 v[90:91], v[90:91], v[126:127] op_sel_hi:[1,0]
	v_pk_mul_f32 v[88:89], v[88:89], v[126:127] op_sel_hi:[1,0]
	v_pk_mul_f32 v[86:87], v[86:87], v[126:127] op_sel_hi:[1,0]
	v_pk_mul_f32 v[84:85], v[84:85], v[126:127] op_sel_hi:[1,0]
	v_pk_mul_f32 v[94:95], v[80:81], v[126:127] op_sel_hi:[1,0]
	v_pk_mul_f32 v[80:81], v[78:79], v[126:127] op_sel_hi:[1,0]
	v_rsq_f32_e32 v126, v76
	s_nop 0
	v_pk_mul_f32 v[74:75], v[74:75], v[126:127] op_sel_hi:[1,0]
	v_pk_mul_f32 v[72:73], v[72:73], v[126:127] op_sel_hi:[1,0]
	v_pk_mul_f32 v[70:71], v[70:71], v[126:127] op_sel_hi:[1,0]
	v_pk_mul_f32 v[68:69], v[68:69], v[126:127] op_sel_hi:[1,0]
	v_pk_mul_f32 v[76:77], v[66:67], v[126:127] op_sel_hi:[1,0]
	v_pk_mul_f32 v[78:79], v[64:65], v[126:127] op_sel_hi:[1,0]
	v_pk_mul_f32 v[64:65], v[62:63], v[126:127] op_sel_hi:[1,0]
	v_pk_mul_f32 v[66:67], v[60:61], v[126:127] op_sel_hi:[1,0]
	v_pk_mul_f32 v[60:61], v[58:59], v[192:193] op_sel_hi:[1,0]
	v_pk_mul_f32 v[58:59], v[52:53], v[192:193]
	v_pk_mul_f32 v[50:51], v[50:51], v[190:191] op_sel_hi:[1,0]
	v_pk_mul_f32 v[46:47], v[46:47], v[190:191] op_sel_hi:[1,0]
	v_pk_mul_f32 v[62:63], v[56:57], v[192:193]
	v_fma_f32 v56, v152, v12, v8
	v_fma_f32 v57, v153, v13, v9
	v_fma_f32 v53, v136, v157, v56
	v_fma_f32 v52, v120, v156, v53
	v_mul_f32_e32 v53, 0xbfb8aa3b, v52
	v_exp_f32_e32 v53, v53
	v_pk_mul_f32 v[54:55], v[54:55], v[192:193] op_sel_hi:[1,0]
	v_fma_f32 v126, v154, v14, v10
	v_add_f32_e32 v53, 1.0, v53
	v_rcp_f32_e32 v53, v53
	s_nop 0
	v_mul_f32_e32 v52, v52, v53
	v_mul_f32_e32 v56, v132, v52
	v_fma_f32 v132, v150, v18, v26
	v_fma_f32 v53, v137, v5, v57
	v_fma_f32 v52, v121, v4, v53
	v_mul_f32_e32 v53, 0xbfb8aa3b, v52
	v_exp_f32_e32 v53, v53
	s_nop 0
	v_add_f32_e32 v53, 1.0, v53
	v_rcp_f32_e32 v53, v53
	s_nop 0
	v_mul_f32_e32 v52, v52, v53
	v_mul_f32_e32 v57, v133, v52
	v_fma_f32 v53, v138, v159, v126
	v_fma_f32 v52, v122, v158, v53
	v_mul_f32_e32 v53, 0xbfb8aa3b, v52
	v_exp_f32_e32 v53, v53
	s_nop 0
	v_add_f32_e32 v53, 1.0, v53
	v_rcp_f32_e32 v53, v53
	s_nop 0
	v_mul_f32_e32 v52, v52, v53
	v_mul_f32_e32 v126, v124, v52
	v_fma_f32 v124, v155, v15, v11
	v_fma_f32 v53, v139, v7, v124
	v_fma_f32 v52, v123, v6, v53
	v_mul_f32_e32 v53, 0xbfb8aa3b, v52
	v_exp_f32_e32 v53, v53
	v_cvt_pk_bf16_f32 v124, v56, v57
	v_add_f32_e32 v53, 1.0, v53
	v_rcp_f32_e32 v53, v53
	s_nop 0
	v_mul_f32_e32 v52, v52, v53
	v_mul_f32_e32 v52, v125, v52
	v_cvt_pk_bf16_f32 v125, v126, v52
	v_mov_b32_e32 v52, v140
	v_mov_b32_e32 v53, v20
	v_fma_f32 v126, v148, v16, v24
	v_fma_f32 v20, v128, v53, v126
	v_fma_f32 v20, v116, v52, v20
	v_mul_f32_e32 v56, 0xbfb8aa3b, v20
	v_exp_f32_e32 v56, v56
	s_nop 0
	v_add_f32_e32 v56, 1.0, v56
	v_rcp_f32_e32 v56, v56
	s_nop 0
	v_mul_f32_e32 v20, v20, v56
	v_mul_f32_e32 v126, v114, v20
	v_mov_b32_e32 v20, v141
	v_fma_f32 v114, v149, v17, v25
	v_fma_f32 v57, v129, v21, v114
	v_fma_f32 v56, v117, v20, v57
	v_mul_f32_e32 v57, 0xbfb8aa3b, v56
	v_exp_f32_e32 v57, v57
	s_nop 0
	v_add_f32_e32 v57, 1.0, v57
	v_rcp_f32_e32 v57, v57
	s_nop 0
	v_mul_f32_e32 v56, v56, v57
	v_mul_f32_e32 v127, v115, v56
	v_mov_b32_e32 v56, v142
	v_mov_b32_e32 v57, v22
	v_cvt_pk_bf16_f32 v126, v126, v127
	s_nop 0
	v_fma_f32 v22, v130, v57, v132
	v_fma_f32 v22, v118, v56, v22
	v_mul_f32_e32 v114, 0xbfb8aa3b, v22
	v_exp_f32_e32 v114, v114
	v_fma_f32 v132, v151, v19, v27
	v_add_f32_e32 v114, 1.0, v114
	v_rcp_f32_e32 v114, v114
	s_nop 0
	v_mul_f32_e32 v22, v22, v114
	v_mul_f32_e32 v112, v112, v22
	v_mov_b32_e32 v22, v143
	v_fma_f32 v115, v131, v23, v132
	v_fma_f32 v114, v119, v22, v115
	v_mul_f32_e32 v115, 0xbfb8aa3b, v114
	v_exp_f32_e32 v115, v115
	s_nop 0
	v_add_f32_e32 v115, 1.0, v115
	v_rcp_f32_e32 v115, v115
	s_nop 0
	v_mul_f32_e32 v114, v114, v115
	v_mul_f32_e32 v113, v113, v114
	v_cvt_pk_bf16_f32 v127, v112, v113
	v_or_b32_e32 v112, 2, v188
	v_mad_i64_i32 v[112:113], s[0:1], v112, s10, v[172:173]
	global_store_dwordx4 v[112:113], v[124:127], off
	v_fma_f32 v114, v12, v136, v8
	v_fma_f32 v113, v120, v157, v114
	v_fma_f32 v112, v104, v156, v113
; __device__ __forceinline__ unsigned cvt_pk_bf16(float lo, float hi) { unsigned r; asm volatile("v_cvt_pk_bf16_f32 %0, %1, %2" : "=v"(r) : "v"(lo), "v"(hi)); return r; }
; __device__ __forceinline__ float siluf_(float x) { return x * __builtin_amdgcn_rcpf(1.f + __expf(-x)); }
;     __device__ __forceinline__ void operator()(f32x4 (&acc)[2][2][4][2], const pg8::Unit& u, int wr, int wc, int fr, int fq) const {
;     ...
;         for (int k = 0; k < 8; ++k) {
;             unsigned hw[4];
; #pragma unroll
;             for (int n = 0; n < 2; ++n) {
;                 const f32x4 uk = acc[k >> 2][0][k & 3][n], gk = acc[k >> 2][1][k & 3][n];
;                 const f32x4 um1 = (k >= 1) ? acc[(k - 1 < 0 ? 0 : k - 1) >> 2][0][(k - 1 < 0 ? 0 : k - 1) & 3][n] : p7[n];
;                 const f32x4 um2 = (k >= 2) ? acc[(k - 2 < 0 ? 0 : k - 2) >> 2][0][(k - 2 < 0 ? 0 : k - 2) & 3][n] : (k == 1 ? p7[n] : p6[n]);
;                 const f32x4 cv = bb[n] + w0[n] * um2 + w1[n] * um1 + w2[n] * uk;
;                 f32x4 hv;
; #pragma unroll
;                 for (int e = 0; e < 4; ++e) hv[e] = siluf_(cv[e]) * gk[e];
;                 hw[2 * n] = pg8::cvt_pk_bf16(hv[0], hv[1]); hw[2 * n + 1] = pg8::cvt_pk_bf16(hv[2], hv[3]);
;                 if (defer && k < 2) {
;                     *(f32x4*)(sbf + (size_t)((grp * 2 + k) * 2 + 0) * DFF + ch0 + 4 * n) = uk;
;                     *(f32x4*)(sbf + (size_t)((grp * 2 + k) * 2 + 1) * DFF + ch0 + 4 * n) = gk;
;                 }
;             }
;             if (!(defer && k < 2)) *(u32x4*)(H + (size_t)(tok0 + k) * DFF + ch0) = (u32x4){hw[0], hw[1], hw[2], hw[3]};
	v_mul_f32_e32 v113, 0xbfb8aa3b, v112
	v_exp_f32_e32 v113, v113
	s_nop 0
	v_add_f32_e32 v113, 1.0, v113
	v_rcp_f32_e32 v113, v113
	s_nop 0
	v_mul_f32_e32 v112, v112, v113
	v_mul_f32_e32 v114, v110, v112
	v_fma_f32 v110, v13, v137, v9
	v_fma_f32 v110, v121, v5, v110
	v_fma_f32 v110, v105, v4, v110
	v_mul_f32_e32 v112, 0xbfb8aa3b, v110
	v_exp_f32_e32 v112, v112
	v_fma_f32 v113, v14, v138, v10
	v_add_f32_e32 v112, 1.0, v112
	v_rcp_f32_e32 v112, v112
	s_nop 0
	v_mul_f32_e32 v110, v110, v112
	v_mul_f32_e32 v112, v111, v110
	v_fma_f32 v111, v122, v159, v113
	v_fma_f32 v110, v106, v158, v111
	v_mul_f32_e32 v111, 0xbfb8aa3b, v110
	v_exp_f32_e32 v111, v111
	s_nop 0
	v_add_f32_e32 v111, 1.0, v111
	v_rcp_f32_e32 v111, v111
	s_nop 0
	v_mul_f32_e32 v110, v110, v111
	v_mul_f32_e32 v113, v108, v110
	v_fma_f32 v108, v15, v139, v11
	v_fma_f32 v108, v123, v7, v108
	v_fma_f32 v108, v107, v6, v108
	v_mul_f32_e32 v110, 0xbfb8aa3b, v108
	v_exp_f32_e32 v110, v110
	s_nop 0
	v_add_f32_e32 v110, 1.0, v110
	v_rcp_f32_e32 v110, v110
	s_nop 0
	v_mul_f32_e32 v108, v108, v110
	v_mul_f32_e32 v109, v109, v108
	v_cvt_pk_bf16_f32 v108, v114, v112
	v_fma_f32 v112, v128, v16, v24
	v_cvt_pk_bf16_f32 v109, v113, v109
	s_nop 0
	v_fma_f32 v111, v116, v53, v112
	v_fma_f32 v110, v100, v52, v111
	v_mul_f32_e32 v111, 0xbfb8aa3b, v110
	v_exp_f32_e32 v111, v111
	s_nop 0
	v_add_f32_e32 v111, 1.0, v111
	v_rcp_f32_e32 v111, v111
	s_nop 0
	v_mul_f32_e32 v110, v110, v111
	v_mul_f32_e32 v112, v98, v110
	v_fma_f32 v98, v129, v17, v25
	v_fma_f32 v98, v117, v21, v98
	v_fma_f32 v98, v101, v20, v98
	v_mul_f32_e32 v110, 0xbfb8aa3b, v98
	v_exp_f32_e32 v110, v110
	v_fma_f32 v111, v130, v18, v26
	v_add_f32_e32 v110, 1.0, v110
	v_rcp_f32_e32 v110, v110
	s_nop 0
	v_mul_f32_e32 v98, v98, v110
	v_mul_f32_e32 v110, v99, v98
	v_cvt_pk_bf16_f32 v110, v112, v110
	s_nop 0
	v_fma_f32 v99, v118, v57, v111
	v_fma_f32 v98, v102, v56, v99
	v_mul_f32_e32 v99, 0xbfb8aa3b, v98
	v_exp_f32_e32 v99, v99
	v_fma_f32 v111, v131, v19, v27
	v_add_f32_e32 v99, 1.0, v99
	v_rcp_f32_e32 v99, v99
	s_nop 0
	v_mul_f32_e32 v98, v98, v99
	v_mul_f32_e32 v96, v96, v98
	v_fma_f32 v99, v119, v23, v111
	v_fma_f32 v98, v103, v22, v99
	v_mul_f32_e32 v99, 0xbfb8aa3b, v98
	v_exp_f32_e32 v99, v99
	s_nop 0
	v_add_f32_e32 v99, 1.0, v99
	v_rcp_f32_e32 v99, v99
	s_nop 0
	v_mul_f32_e32 v98, v98, v99
	v_mul_f32_e32 v97, v97, v98
	v_cvt_pk_bf16_f32 v111, v96, v97
	v_or_b32_e32 v96, 3, v188
	v_mad_i64_i32 v[96:97], s[0:1], v96, s10, v[172:173]
	global_store_dwordx4 v[96:97], v[108:111], off
	v_fma_f32 v98, v12, v120, v8
	v_fma_f32 v97, v104, v157, v98
	v_fma_f32 v96, v88, v156, v97
	v_mul_f32_e32 v97, 0xbfb8aa3b, v96
	v_exp_f32_e32 v97, v97
	s_nop 0
	v_add_f32_e32 v97, 1.0, v97
	v_rcp_f32_e32 v97, v97
	s_nop 0
	v_mul_f32_e32 v96, v96, v97
	v_mul_f32_e32 v98, v94, v96
	v_fma_f32 v94, v13, v121, v9
	v_fma_f32 v94, v105, v5, v94
	v_fma_f32 v94, v89, v4, v94
	v_mul_f32_e32 v96, 0xbfb8aa3b, v94
	v_exp_f32_e32 v96, v96
	v_fma_f32 v97, v14, v122, v10
	v_add_f32_e32 v96, 1.0, v96
	v_rcp_f32_e32 v96, v96
	s_nop 0
	v_mul_f32_e32 v94, v94, v96
	v_mul_f32_e32 v96, v95, v94
	v_fma_f32 v95, v106, v159, v97
	v_fma_f32 v94, v90, v158, v95
	v_mul_f32_e32 v95, 0xbfb8aa3b, v94
	v_exp_f32_e32 v95, v95
	s_nop 0
	v_add_f32_e32 v95, 1.0, v95
	v_rcp_f32_e32 v95, v95
	s_nop 0
	v_mul_f32_e32 v94, v94, v95
	v_mul_f32_e32 v97, v92, v94
	v_fma_f32 v92, v15, v123, v11
	v_fma_f32 v92, v107, v7, v92
	v_fma_f32 v92, v91, v6, v92
	v_mul_f32_e32 v94, 0xbfb8aa3b, v92
	v_exp_f32_e32 v94, v94
	s_nop 0
	v_add_f32_e32 v94, 1.0, v94
	v_rcp_f32_e32 v94, v94
	s_nop 0
	v_mul_f32_e32 v92, v92, v94
	v_mul_f32_e32 v93, v93, v92
	v_cvt_pk_bf16_f32 v92, v98, v96
	v_fma_f32 v96, v116, v16, v24
	v_cvt_pk_bf16_f32 v93, v97, v93
	s_nop 0
	v_fma_f32 v95, v100, v53, v96
	v_fma_f32 v94, v84, v52, v95
	v_mul_f32_e32 v95, 0xbfb8aa3b, v94
	v_exp_f32_e32 v95, v95
	s_nop 0
	v_add_f32_e32 v95, 1.0, v95
	v_rcp_f32_e32 v95, v95
	s_nop 0
	v_mul_f32_e32 v94, v94, v95
	v_mul_f32_e32 v96, v82, v94
	v_fma_f32 v82, v117, v17, v25
	v_fma_f32 v82, v101, v21, v82
	v_fma_f32 v82, v85, v20, v82
	v_mul_f32_e32 v94, 0xbfb8aa3b, v82
	v_exp_f32_e32 v94, v94
	v_fma_f32 v95, v118, v18, v26
	v_add_f32_e32 v94, 1.0, v94
	v_rcp_f32_e32 v94, v94
	s_nop 0
	v_mul_f32_e32 v82, v82, v94
	v_mul_f32_e32 v94, v83, v82
	v_cvt_pk_bf16_f32 v94, v96, v94
	s_nop 0
	v_fma_f32 v83, v102, v57, v95
	v_fma_f32 v82, v86, v56, v83
	v_mul_f32_e32 v83, 0xbfb8aa3b, v82
	v_exp_f32_e32 v83, v83
	v_fma_f32 v95, v119, v19, v27
	v_add_f32_e32 v83, 1.0, v83
	v_rcp_f32_e32 v83, v83
	s_nop 0
	v_mul_f32_e32 v82, v82, v83
	v_mul_f32_e32 v80, v80, v82
	v_fma_f32 v83, v103, v23, v95
	v_fma_f32 v82, v87, v22, v83
	v_mul_f32_e32 v83, 0xbfb8aa3b, v82
	v_exp_f32_e32 v83, v83
	s_nop 0
	v_add_f32_e32 v83, 1.0, v83
	v_rcp_f32_e32 v83, v83
	s_nop 0
	v_mul_f32_e32 v82, v82, v83
	v_mul_f32_e32 v81, v81, v82
	v_cvt_pk_bf16_f32 v95, v80, v81
	v_or_b32_e32 v80, 4, v188
	v_mad_i64_i32 v[80:81], s[0:1], v80, s10, v[172:173]
	global_store_dwordx4 v[80:81], v[92:95], off
	v_fma_f32 v82, v12, v104, v8
	v_fma_f32 v81, v88, v157, v82
	v_fma_f32 v80, v72, v156, v81
	v_mul_f32_e32 v81, 0xbfb8aa3b, v80
	v_exp_f32_e32 v81, v81
	s_nop 0
	v_add_f32_e32 v81, 1.0, v81
	v_rcp_f32_e32 v81, v81
	s_nop 0
	v_mul_f32_e32 v80, v80, v81
	v_mul_f32_e32 v82, v78, v80
	v_fma_f32 v78, v13, v105, v9
	v_fma_f32 v78, v89, v5, v78
	v_fma_f32 v78, v73, v4, v78
	v_mul_f32_e32 v80, 0xbfb8aa3b, v78
	v_exp_f32_e32 v80, v80
	v_fma_f32 v81, v14, v106, v10
	v_add_f32_e32 v80, 1.0, v80
	v_rcp_f32_e32 v80, v80
	s_nop 0
	v_mul_f32_e32 v78, v78, v80
	v_mul_f32_e32 v80, v79, v78
	v_fma_f32 v79, v90, v159, v81
; __device__ __forceinline__ unsigned cvt_pk_bf16(float lo, float hi) { unsigned r; asm volatile("v_cvt_pk_bf16_f32 %0, %1, %2" : "=v"(r) : "v"(lo), "v"(hi)); return r; }
; __device__ __forceinline__ float siluf_(float x) { return x * __builtin_amdgcn_rcpf(1.f + __expf(-x)); }
;     __device__ __forceinline__ void operator()(f32x4 (&acc)[2][2][4][2], const pg8::Unit& u, int wr, int wc, int fr, int fq) const {
;     ...
;         for (int k = 0; k < 8; ++k) {
;             unsigned hw[4];
; #pragma unroll
;             for (int n = 0; n < 2; ++n) {
;                 const f32x4 uk = acc[k >> 2][0][k & 3][n], gk = acc[k >> 2][1][k & 3][n];
;                 const f32x4 um1 = (k >= 1) ? acc[(k - 1 < 0 ? 0 : k - 1) >> 2][0][(k - 1 < 0 ? 0 : k - 1) & 3][n] : p7[n];
;                 const f32x4 um2 = (k >= 2) ? acc[(k - 2 < 0 ? 0 : k - 2) >> 2][0][(k - 2 < 0 ? 0 : k - 2) & 3][n] : (k == 1 ? p7[n] : p6[n]);
;                 const f32x4 cv = bb[n] + w0[n] * um2 + w1[n] * um1 + w2[n] * uk;
;                 f32x4 hv;
; #pragma unroll
;                 for (int e = 0; e < 4; ++e) hv[e] = siluf_(cv[e]) * gk[e];
;                 hw[2 * n] = pg8::cvt_pk_bf16(hv[0], hv[1]); hw[2 * n + 1] = pg8::cvt_pk_bf16(hv[2], hv[3]);
;                 if (defer && k < 2) {
;                     *(f32x4*)(sbf + (size_t)((grp * 2 + k) * 2 + 0) * DFF + ch0 + 4 * n) = uk;
;                     *(f32x4*)(sbf + (size_t)((grp * 2 + k) * 2 + 1) * DFF + ch0 + 4 * n) = gk;
;                 }
;             }
;             if (!(defer && k < 2)) *(u32x4*)(H + (size_t)(tok0 + k) * DFF + ch0) = (u32x4){hw[0], hw[1], hw[2], hw[3]};
	v_fma_f32 v78, v74, v158, v79
	v_mul_f32_e32 v79, 0xbfb8aa3b, v78
	v_exp_f32_e32 v79, v79
	s_nop 0
	v_add_f32_e32 v79, 1.0, v79
	v_rcp_f32_e32 v79, v79
	s_nop 0
	v_mul_f32_e32 v78, v78, v79
	v_mul_f32_e32 v81, v76, v78
	v_fma_f32 v76, v15, v107, v11
	v_fma_f32 v76, v91, v7, v76
	v_fma_f32 v76, v75, v6, v76
	v_mul_f32_e32 v78, 0xbfb8aa3b, v76
	v_exp_f32_e32 v78, v78
	s_nop 0
	v_add_f32_e32 v78, 1.0, v78
	v_rcp_f32_e32 v78, v78
	s_nop 0
	v_mul_f32_e32 v76, v76, v78
	v_mul_f32_e32 v77, v77, v76
	v_cvt_pk_bf16_f32 v76, v82, v80
	v_fma_f32 v80, v100, v16, v24
	v_cvt_pk_bf16_f32 v77, v81, v77
	s_nop 0
	v_fma_f32 v79, v84, v53, v80
	v_fma_f32 v78, v68, v52, v79
	v_mul_f32_e32 v79, 0xbfb8aa3b, v78
	v_exp_f32_e32 v79, v79
	s_nop 0
	v_add_f32_e32 v79, 1.0, v79
	v_rcp_f32_e32 v79, v79
	s_nop 0
	v_mul_f32_e32 v78, v78, v79
	v_mul_f32_e32 v80, v66, v78
	v_fma_f32 v66, v101, v17, v25
	v_fma_f32 v66, v85, v21, v66
	v_fma_f32 v66, v69, v20, v66
	v_mul_f32_e32 v78, 0xbfb8aa3b, v66
	v_exp_f32_e32 v78, v78
	v_fma_f32 v79, v102, v18, v26
	v_add_f32_e32 v78, 1.0, v78
	v_rcp_f32_e32 v78, v78
	s_nop 0
	v_mul_f32_e32 v66, v66, v78
	v_mul_f32_e32 v78, v67, v66
	v_cvt_pk_bf16_f32 v78, v80, v78
	s_nop 0
	v_fma_f32 v67, v86, v57, v79
	v_fma_f32 v66, v70, v56, v67
	v_mul_f32_e32 v67, 0xbfb8aa3b, v66
	v_exp_f32_e32 v67, v67
	v_fma_f32 v79, v103, v19, v27
	v_add_f32_e32 v67, 1.0, v67
	v_rcp_f32_e32 v67, v67
	s_nop 0
	v_mul_f32_e32 v66, v66, v67
	v_mul_f32_e32 v64, v64, v66
	v_fma_f32 v67, v87, v23, v79
	v_fma_f32 v66, v71, v22, v67
	v_mul_f32_e32 v67, 0xbfb8aa3b, v66
	v_exp_f32_e32 v67, v67
	s_nop 0
	v_add_f32_e32 v67, 1.0, v67
	v_rcp_f32_e32 v67, v67
	s_nop 0
	v_mul_f32_e32 v66, v66, v67
	v_mul_f32_e32 v65, v65, v66
	v_cvt_pk_bf16_f32 v79, v64, v65
	v_or_b32_e32 v64, 5, v188
	v_mad_i64_i32 v[64:65], s[0:1], v64, s10, v[172:173]
	global_store_dwordx4 v[64:65], v[76:79], off
	v_fma_f32 v66, v12, v88, v8
	v_fma_f32 v8, v12, v72, v8
	v_fma_f32 v65, v72, v157, v66
	v_fma_f32 v64, v28, v156, v65
	v_mul_f32_e32 v65, 0xbfb8aa3b, v64
	v_exp_f32_e32 v65, v65
	s_nop 0
	v_add_f32_e32 v65, 1.0, v65
	v_rcp_f32_e32 v65, v65
	s_nop 0
	v_mul_f32_e32 v64, v64, v65
	v_mul_f32_e32 v66, v62, v64
	v_fma_f32 v62, v13, v89, v9
	v_fma_f32 v9, v13, v73, v9
	v_fma_f32 v62, v73, v5, v62
	v_fma_f32 v62, v29, v4, v62
	v_mul_f32_e32 v64, 0xbfb8aa3b, v62
	v_exp_f32_e32 v64, v64
	v_fma_f32 v65, v14, v90, v10
	v_fma_f32 v10, v14, v74, v10
	v_add_f32_e32 v64, 1.0, v64
	v_rcp_f32_e32 v64, v64
	s_nop 0
	v_mul_f32_e32 v62, v62, v64
	v_mul_f32_e32 v64, v63, v62
	v_fma_f32 v63, v74, v159, v65
	v_fma_f32 v62, v30, v158, v63
	v_mul_f32_e32 v63, 0xbfb8aa3b, v62
	v_exp_f32_e32 v63, v63
	s_nop 0
	v_add_f32_e32 v63, 1.0, v63
	v_rcp_f32_e32 v63, v63
	s_nop 0
	v_mul_f32_e32 v62, v62, v63
	v_mul_f32_e32 v65, v60, v62
	v_fma_f32 v60, v15, v91, v11
	v_fmac_f32_e32 v11, v15, v75
	v_fma_f32 v60, v75, v7, v60
	v_fma_f32 v60, v31, v6, v60
	v_mul_f32_e32 v62, 0xbfb8aa3b, v60
	v_exp_f32_e32 v62, v62
	s_nop 0
	v_add_f32_e32 v62, 1.0, v62
	v_rcp_f32_e32 v62, v62
	s_nop 0
	v_mul_f32_e32 v60, v60, v62
	v_mul_f32_e32 v61, v61, v60
	v_cvt_pk_bf16_f32 v60, v66, v64
	v_fma_f32 v64, v84, v16, v24
	v_cvt_pk_bf16_f32 v61, v65, v61
	s_nop 0
	v_fma_f32 v63, v68, v53, v64
	v_fma_f32 v62, v32, v52, v63
	v_mul_f32_e32 v63, 0xbfb8aa3b, v62
	v_exp_f32_e32 v63, v63
	s_nop 0
	v_add_f32_e32 v63, 1.0, v63
	v_rcp_f32_e32 v63, v63
	s_nop 0
	v_mul_f32_e32 v62, v62, v63
	v_mul_f32_e32 v64, v58, v62
	v_fma_f32 v58, v85, v17, v25
	v_fma_f32 v58, v69, v21, v58
	v_fma_f32 v58, v33, v20, v58
	v_mul_f32_e32 v62, 0xbfb8aa3b, v58
	v_exp_f32_e32 v62, v62
	v_fma_f32 v63, v86, v18, v26
	v_add_f32_e32 v62, 1.0, v62
	v_rcp_f32_e32 v62, v62
; __device__ __forceinline__ unsigned cvt_pk_bf16(float lo, float hi) { unsigned r; asm volatile("v_cvt_pk_bf16_f32 %0, %1, %2" : "=v"(r) : "v"(lo), "v"(hi)); return r; }
; __device__ __forceinline__ float siluf_(float x) { return x * __builtin_amdgcn_rcpf(1.f + __expf(-x)); }
;     __device__ __forceinline__ void operator()(f32x4 (&acc)[2][2][4][2], const pg8::Unit& u, int wr, int wc, int fr, int fq) const {
;     ...
;         for (int k = 0; k < 8; ++k) {
;             unsigned hw[4];
; #pragma unroll
;             for (int n = 0; n < 2; ++n) {
;                 const f32x4 uk = acc[k >> 2][0][k & 3][n], gk = acc[k >> 2][1][k & 3][n];
;                 const f32x4 um1 = (k >= 1) ? acc[(k - 1 < 0 ? 0 : k - 1) >> 2][0][(k - 1 < 0 ? 0 : k - 1) & 3][n] : p7[n];
;                 const f32x4 um2 = (k >= 2) ? acc[(k - 2 < 0 ? 0 : k - 2) >> 2][0][(k - 2 < 0 ? 0 : k - 2) & 3][n] : (k == 1 ? p7[n] : p6[n]);
;                 const f32x4 cv = bb[n] + w0[n] * um2 + w1[n] * um1 + w2[n] * uk;
;                 f32x4 hv;
; #pragma unroll
;                 for (int e = 0; e < 4; ++e) hv[e] = siluf_(cv[e]) * gk[e];
;                 hw[2 * n] = pg8::cvt_pk_bf16(hv[0], hv[1]); hw[2 * n + 1] = pg8::cvt_pk_bf16(hv[2], hv[3]);
;                 if (defer && k < 2) {
;                     *(f32x4*)(sbf + (size_t)((grp * 2 + k) * 2 + 0) * DFF + ch0 + 4 * n) = uk;
;                     *(f32x4*)(sbf + (size_t)((grp * 2 + k) * 2 + 1) * DFF + ch0 + 4 * n) = gk;
;                 }
;             }
;             if (!(defer && k < 2)) *(u32x4*)(H + (size_t)(tok0 + k) * DFF + ch0) = (u32x4){hw[0], hw[1], hw[2], hw[3]};
;         }
	s_nop 0
	v_mul_f32_e32 v58, v58, v62
	v_mul_f32_e32 v62, v59, v58
	v_cvt_pk_bf16_f32 v62, v64, v62
	s_nop 0
	v_fma_f32 v59, v70, v57, v63
	v_fma_f32 v58, v34, v56, v59
	v_mul_f32_e32 v59, 0xbfb8aa3b, v58
	v_exp_f32_e32 v59, v59
	v_fma_f32 v63, v87, v19, v27
	v_fmac_f32_e32 v27, v71, v19
	v_add_f32_e32 v59, 1.0, v59
	v_rcp_f32_e32 v59, v59
	s_nop 0
	v_mul_f32_e32 v58, v58, v59
	v_mul_f32_e32 v54, v54, v58
	v_fma_f32 v59, v71, v23, v63
	v_fma_f32 v58, v35, v22, v59
	v_mul_f32_e32 v59, 0xbfb8aa3b, v58
	v_exp_f32_e32 v59, v59
	s_nop 0
	v_add_f32_e32 v59, 1.0, v59
	v_rcp_f32_e32 v59, v59
	s_nop 0
	v_mul_f32_e32 v58, v58, v59
	v_mul_f32_e32 v55, v55, v58
	v_cvt_pk_bf16_f32 v63, v54, v55
	v_or_b32_e32 v54, 6, v188
	v_mad_i64_i32 v[54:55], s[0:1], v54, s10, v[172:173]
	global_store_dwordx4 v[54:55], v[60:63], off
	v_mov_b32_e32 v55, v28
	v_mov_b32_e32 v28, v37
	v_pk_mul_f32 v[4:5], v[4:5], v[28:29]
	v_mov_b32_e32 v54, v36
	v_add_f32_e32 v5, v5, v9
	v_add_f32_e32 v4, v4, v5
	v_mul_f32_e32 v5, 0xbfb8aa3b, v4
	v_exp_f32_e32 v5, v5
	v_pk_mul_f32 v[54:55], v[156:157], v[54:55]
	v_add_f32_e32 v5, 1.0, v5
	v_rcp_f32_e32 v5, v5
	v_add_f32_e32 v8, v55, v8
	v_add_f32_e32 v8, v54, v8
	v_mul_f32_e32 v12, 0xbfb8aa3b, v8
	v_mul_f32_e32 v4, v4, v5
	v_mul_f32_e32 v9, v49, v4
	v_mov_b32_e32 v4, v38
	v_mov_b32_e32 v5, v30
	v_pk_mul_f32 v[4:5], v[158:159], v[4:5]
	v_mov_b32_e32 v30, v39
	v_add_f32_e32 v5, v5, v10
	v_add_f32_e32 v4, v4, v5
	v_mul_f32_e32 v5, 0xbfb8aa3b, v4
	v_exp_f32_e32 v5, v5
	v_exp_f32_e32 v12, v12
	v_add_f32_e32 v5, 1.0, v5
	v_rcp_f32_e32 v5, v5
	v_add_f32_e32 v12, 1.0, v12
	v_rcp_f32_e32 v12, v12
	v_mul_f32_e32 v4, v4, v5
	v_mul_f32_e32 v10, v50, v4
	v_pk_mul_f32 v[4:5], v[6:7], v[30:31]
	v_mul_f32_e32 v8, v8, v12
	v_add_f32_e32 v5, v5, v11
	v_add_f32_e32 v4, v4, v5
	v_mul_f32_e32 v5, 0xbfb8aa3b, v4
	v_exp_f32_e32 v5, v5
	v_mul_f32_e32 v8, v48, v8
	v_mov_b32_e32 v6, v40
	v_mov_b32_e32 v7, v32
	v_add_f32_e32 v5, 1.0, v5
	v_rcp_f32_e32 v5, v5
	v_pk_mul_f32 v[6:7], v[6:7], v[52:53]
	v_mov_b32_e32 v32, v41
	v_mul_f32_e32 v4, v4, v5
	v_mul_f32_e32 v5, v51, v4
	v_cvt_pk_bf16_f32 v4, v8, v9
	v_fma_f32 v8, v68, v16, v24
	v_add_f32_e32 v7, v7, v8
	v_add_f32_e32 v6, v6, v7
	v_mul_f32_e32 v7, 0xbfb8aa3b, v6
	v_exp_f32_e32 v7, v7
	v_fma_f32 v9, v69, v17, v25
	v_cvt_pk_bf16_f32 v5, v10, v5
	v_fma_f32 v10, v70, v18, v26
	v_add_f32_e32 v7, 1.0, v7
	v_rcp_f32_e32 v7, v7
	s_nop 0
	v_mul_f32_e32 v6, v6, v7
	v_mul_f32_e32 v8, v44, v6
	v_pk_mul_f32 v[6:7], v[32:33], v[20:21]
	s_nop 0
	v_add_f32_e32 v7, v7, v9
	v_add_f32_e32 v6, v6, v7
	v_mul_f32_e32 v7, 0xbfb8aa3b, v6
	v_exp_f32_e32 v7, v7
	s_nop 0
	v_add_f32_e32 v7, 1.0, v7
	v_rcp_f32_e32 v7, v7
	s_nop 0
	v_mul_f32_e32 v6, v6, v7
	v_mul_f32_e32 v9, v45, v6
	v_mov_b32_e32 v6, v42
	v_mov_b32_e32 v7, v34
	v_pk_mul_f32 v[6:7], v[6:7], v[56:57]
	v_mov_b32_e32 v34, v43
	v_add_f32_e32 v7, v7, v10
	v_add_f32_e32 v6, v6, v7
	v_mul_f32_e32 v7, 0xbfb8aa3b, v6
	v_exp_f32_e32 v7, v7
	s_nop 0
	v_add_f32_e32 v7, 1.0, v7
	v_rcp_f32_e32 v7, v7
	s_nop 0
	v_mul_f32_e32 v6, v6, v7
	v_mul_f32_e32 v10, v46, v6
	v_pk_mul_f32 v[6:7], v[34:35], v[22:23]
	s_nop 0
	v_add_f32_e32 v7, v7, v27
	v_add_f32_e32 v6, v6, v7
	v_mul_f32_e32 v7, 0xbfb8aa3b, v6
	v_exp_f32_e32 v7, v7
	s_nop 0
	v_add_f32_e32 v7, 1.0, v7
	v_rcp_f32_e32 v7, v7
	s_nop 0
	v_mul_f32_e32 v6, v6, v7
	v_mul_f32_e32 v7, v47, v6
	v_cvt_pk_bf16_f32 v6, v8, v9
	v_or_b32_e32 v8, 7, v188
	v_mad_i64_i32 v[8:9], s[0:1], v8, s10, v[172:173]
	s_mov_b64 s[0:1], -1
	v_cvt_pk_bf16_f32 v7, v10, v7
	global_store_dwordx4 v[8:9], v[4:7], off
	s_cbranch_vccnz .LBB0_462
	s_andn2_b64 vcc, exec, s[22:23]
	s_cbranch_vccnz .LBB0_461
	s_barrier
	s_branch .LBB0_461
